# NA latent loop: inline-asm pads between v_max3 links removed, post-QK^T pad 24 -> 10 states (>= 12 with the surrounding SALU on the shortest path)
# speedup vs baseline: 1.0007x; 1.0007x over previous
; __device__ __forceinline__ float xor32_max(float x) { auto rr = __builtin_amdgcn_permlane32_swap(__float_as_uint(x), __float_as_uint(x), false, false); return fmaxf(__uint_as_float(rr[0]), __uint_as_float(rr[1])); }
; __device__ __forceinline__ float max3f_(float a, float b, float c) { float r; asm("v_max3_f32 %0, %1, %2, %3" : "=v"(r) : "v"(a), "v"(b), "v"(c)); return r; }
; template <int KW, int DV, bool NA> ...
;     ...
;         asm volatile("s_nop 15\n\ts_nop 7" : "+v"(p0), "+v"(p1));
;         float mxa = max3f_(p0[0], p0[1], p1[0]), mxb = max3f_(p0[2], p0[3], p1[1]);
;         mxa = max3f_(mxa, p1[2], p1[3]);
; #pragma unroll
;         for (int r = 4; r < 16; r += 4) { mxa = max3f_(mxa, p0[r], p0[r + 1]); mxb = max3f_(mxb, p0[r + 2], p0[r + 3]); mxa = max3f_(mxa, p1[r], p1[r + 1]); mxb = max3f_(mxb, p1[r + 2], p1[r + 3]); }
;         float mx = max3f_(mxa, mxb, mxb);
;         mx = xor32_max(mx);
;         if (first || __any(mx > 6.f)) {
.LBB0_499:
	s_or_b64 exec, exec, s[0:1]
	s_nop 9
	s_xor_b64 s[82:83], s[22:23], -1
	v_max3_f32 v82, v66, v67, v50
	v_max3_f32 v83, v68, v69, v51
	s_mov_b64 s[0:1], 0
	v_max3_f32 v82, v82, v52, v53
	v_max3_f32 v83, v83, v72, v73
	v_max3_f32 v82, v82, v70, v71
	v_max3_f32 v83, v83, v56, v57
	v_max3_f32 v82, v82, v54, v55
	v_max3_f32 v83, v83, v76, v77
	v_max3_f32 v82, v82, v74, v75
	v_max3_f32 v83, v83, v60, v61
	v_max3_f32 v82, v82, v58, v59
	v_max3_f32 v83, v83, v80, v81
	v_max3_f32 v82, v82, v78, v79
	v_max3_f32 v83, v83, v64, v65
	v_max3_f32 v82, v82, v62, v63
	v_max3_f32 v82, v82, v83, v83
	v_mov_b32_e32 v83, v82
	s_nop 1
	v_permlane32_swap_b32_e32 v82, v83
	v_max_f32_e32 v83, v83, v83
	v_max_f32_e32 v82, v82, v82
	v_max_f32_e32 v82, v82, v83
	s_and_saveexec_b64 s[26:27], s[82:83]
	s_xor_b64 s[82:83], exec, s[26:27]
	s_cbranch_execnz .LBB0_581
	s_andn2_saveexec_b64 s[82:83], s[82:83]
	s_cbranch_execnz .LBB0_582

; __device__ __forceinline__ float xor32_max(float x) { auto rr = __builtin_amdgcn_permlane32_swap(__float_as_uint(x), __float_as_uint(x), false, false); return fmaxf(__uint_as_float(rr[0]), __uint_as_float(rr[1])); }
; __device__ __forceinline__ float max3f_(float a, float b, float c) { float r; asm("v_max3_f32 %0, %1, %2, %3" : "=v"(r) : "v"(a), "v"(b), "v"(c)); return r; }
; template <int KW, int DV, bool NA> ...
;     ...
;         asm volatile("s_nop 15\n\ts_nop 7" : "+v"(p0), "+v"(p1));
;         float mxa = max3f_(p0[0], p0[1], p1[0]), mxb = max3f_(p0[2], p0[3], p1[1]);
;         mxa = max3f_(mxa, p1[2], p1[3]);
; #pragma unroll
;         for (int r = 4; r < 16; r += 4) { mxa = max3f_(mxa, p0[r], p0[r + 1]); mxb = max3f_(mxb, p0[r + 2], p0[r + 3]); mxa = max3f_(mxa, p1[r], p1[r + 1]); mxb = max3f_(mxb, p1[r + 2], p1[r + 3]); }
;         float mx = max3f_(mxa, mxb, mxb);
;         mx = xor32_max(mx);
;         if (first || __any(mx > 6.f)) {
.LBB0_578:
	s_or_b64 exec, exec, s[74:75]
	s_nop 9
	s_xor_b64 s[74:75], s[22:23], -1
	v_max3_f32 v82, v66, v67, v50
	v_max3_f32 v83, v68, v69, v51
	s_mov_b64 s[0:1], 0
	v_max3_f32 v82, v82, v52, v53
	v_max3_f32 v83, v83, v72, v73
	v_max3_f32 v82, v82, v70, v71
	v_max3_f32 v83, v83, v56, v57
	v_max3_f32 v82, v82, v54, v55
	v_max3_f32 v83, v83, v76, v77
	v_max3_f32 v82, v82, v74, v75
	v_max3_f32 v83, v83, v60, v61
	v_max3_f32 v82, v82, v58, v59
	v_max3_f32 v83, v83, v80, v81
	v_max3_f32 v82, v82, v78, v79
	v_max3_f32 v83, v83, v64, v65
	v_max3_f32 v82, v82, v62, v63
	v_max3_f32 v82, v82, v83, v83
	v_mov_b32_e32 v83, v82
	s_nop 1
	v_permlane32_swap_b32_e32 v82, v83
	v_max_f32_e32 v83, v83, v83
	v_max_f32_e32 v82, v82, v82
	v_max_f32_e32 v82, v82, v83
	s_and_saveexec_b64 s[6:7], s[74:75]
	s_xor_b64 s[74:75], exec, s[6:7]
	s_cbranch_execnz .LBB0_583
	s_andn2_saveexec_b64 s[74:75], s[74:75]
	s_cbranch_execnz .LBB0_584
